# attention loops: LDS-DMA pieces issued inside the PV phase instead of behind the V-fragment reads
# speedup vs baseline: 1.0102x; 1.0007x over previous
.LBB0_541:
	v_mfma_f32_32x32x16_bf16 v[130:145], v[114:117], v[190:193], v[66:81]
	v_add_f32_e32 v118, v98, v99
	v_add_f32_e32 v118, v100, v118
	v_add_f32_e32 v118, v101, v118
	s_lshl_b32 s18, s18, 1
	v_add_f32_e32 v118, v102, v118
	v_add_u32_e32 v243, s18, v238
	v_add_f32_e32 v114, v103, v118
	v_cvt_pk_bf16_f32 v174, v98, v99
	v_cvt_pk_bf16_f32 v175, v100, v101
	s_nop 0
	v_add_f32_e32 v98, v104, v114
	v_mfma_f32_32x32x16_bf16 v[114:129], v[198:201], v[190:193], v[66:81]
	v_add_f32_e32 v98, v105, v98
	v_add_f32_e32 v98, v106, v98
	v_add_f32_e32 v98, v107, v98
	v_cvt_pk_bf16_f32 v176, v102, v103
	v_cvt_pk_bf16_f32 v177, v104, v105
	v_mfma_f32_32x32x16_bf16 v[130:145], v[202:205], v[186:189], v[130:145]
	v_add_f32_e32 v98, v108, v98
	v_add_f32_e32 v98, v109, v98
	v_add_f32_e32 v98, v110, v98
	v_add_f32_e32 v98, v111, v98
	v_cvt_pk_bf16_f32 v170, v106, v107
	v_cvt_pk_bf16_f32 v171, v108, v109
	v_mfma_f32_32x32x16_bf16 v[114:129], v[194:197], v[186:189], v[114:129]
	v_add_f32_e32 v98, v112, v98
	v_add_f32_e32 v98, v113, v98
	v_add_f32_e32 v98, v82, v98
	v_add_f32_e32 v98, v83, v98
	v_cvt_pk_bf16_f32 v172, v110, v111
	v_cvt_pk_bf16_f32 v173, v112, v113
	v_mfma_f32_32x32x16_bf16 v[130:145], v[158:161], v[182:185], v[130:145]
	v_add_f32_e32 v98, v84, v98
	v_add_f32_e32 v98, v85, v98
	v_add_f32_e32 v98, v86, v98
	v_add_f32_e32 v98, v87, v98
	v_cvt_pk_bf16_f32 v166, v82, v83
	v_cvt_pk_bf16_f32 v167, v84, v85
	v_mfma_f32_32x32x16_bf16 v[114:129], v[154:157], v[182:185], v[114:129]
	v_add_f32_e32 v82, v88, v98
	v_add_f32_e32 v82, v89, v82
	v_add_f32_e32 v82, v90, v82
	v_add_f32_e32 v82, v91, v82
	v_cvt_pk_bf16_f32 v168, v86, v87
	v_cvt_pk_bf16_f32 v169, v88, v89
	v_mfma_f32_32x32x16_bf16 v[130:145], v[150:153], v[178:181], v[130:145]
	v_add_f32_e32 v82, v92, v82
	v_add_f32_e32 v82, v93, v82
	v_add_f32_e32 v82, v94, v82
	v_add_f32_e32 v82, v95, v82
	v_cvt_pk_bf16_f32 v162, v90, v91
	v_cvt_pk_bf16_f32 v163, v92, v93
	v_mfma_f32_32x32x16_bf16 v[114:129], v[146:149], v[178:181], v[114:129]
	v_add_f32_e32 v82, v96, v82
	v_add_f32_e32 v82, v97, v82
	v_add_f32_e32 v242, v242, v82
	v_cvt_pk_bf16_f32 v164, v94, v95
	v_cvt_pk_bf16_f32 v165, v96, v97
	ds_read_b64_tr_b16 v[110:111], v243 offset:24576
	ds_read_b64_tr_b16 v[112:113], v243 offset:25088
	ds_read_b64_tr_b16 v[102:103], v243 offset:25600
	ds_read_b64_tr_b16 v[104:105], v243 offset:26112
	ds_read_b64_tr_b16 v[106:107], v243 offset:28672
	ds_read_b64_tr_b16 v[108:109], v243 offset:29184
	ds_read_b64_tr_b16 v[98:99], v243 offset:29696
	ds_read_b64_tr_b16 v[100:101], v243 offset:30208
	ds_read_b64_tr_b16 v[94:95], v243 offset:26624
	ds_read_b64_tr_b16 v[96:97], v243 offset:27136
	ds_read_b64_tr_b16 v[86:87], v243 offset:27648
	ds_read_b64_tr_b16 v[88:89], v243 offset:28160
	ds_read_b64_tr_b16 v[90:91], v243 offset:30720
	ds_read_b64_tr_b16 v[92:93], v243 offset:31232
	ds_read_b64_tr_b16 v[82:83], v243 offset:31744
	ds_read_b64_tr_b16 v[84:85], v243 offset:32256
	v_subrev_u32_e32 v216, s100, v212
	s_lshl_b32 s45, s33, 1
	v_max3_f32 v146, v130, v131, v132
	v_max3_f32 v147, v133, v134, v135
	v_max3_f32 v146, v146, v136, v137
	v_max3_f32 v147, v147, v138, v139
	v_max3_f32 v146, v146, v140, v141
	v_max3_f32 v147, v147, v142, v143
	v_max3_f32 v146, v146, v144, v145
	v_max3_f32 v147, v147, v114, v115
	v_max3_f32 v146, v146, v116, v117
	v_max3_f32 v147, v147, v118, v119
	v_max3_f32 v146, v146, v120, v121
	v_max3_f32 v147, v147, v122, v123
	v_max3_f32 v146, v146, v124, v125
	v_max3_f32 v147, v147, v126, v127
	v_max3_f32 v146, v146, v128, v129
	v_max_f32_e32 v146, v146, v147
	v_mov_b32_e32 v147, v146
	s_nop 1
	v_permlane32_swap_b32_e32 v146, v147
	v_max_f32_e32 v146, v146, v147
	v_cmp_lt_f32_e32 vcc, s15, v146
	s_cmp_lg_u64 vcc, 0
	s_cselect_b64 s[18:19], -1, 0
	s_cbranch_vccnz .LBB0_549
.LBB0_542:
	s_waitcnt lgkmcnt(14)
	v_mfma_f32_32x32x16_bf16 v[2:17], v[174:177], v[110:113], v[2:17]
	ds_read_b64_tr_b16 v[110:111], v243 offset:32768
	ds_read_b64_tr_b16 v[112:113], v243 offset:33280
	v_exp_f32_e32 v130, v130
	v_exp_f32_e32 v131, v131
	s_waitcnt lgkmcnt(12)
	v_mfma_f32_32x32x16_bf16 v[50:65], v[174:177], v[106:109], v[50:65]
	ds_read_b64_tr_b16 v[106:107], v243 offset:36864
	ds_read_b64_tr_b16 v[108:109], v243 offset:37376
	v_exp_f32_e32 v132, v132
	v_exp_f32_e32 v133, v133
	v_mfma_f32_32x32x16_bf16 v[2:17], v[170:173], v[102:105], v[2:17]
	ds_read_b64_tr_b16 v[102:103], v243 offset:33792
	ds_read_b64_tr_b16 v[104:105], v243 offset:34304
	v_exp_f32_e32 v134, v134
	v_exp_f32_e32 v135, v135
	s_waitcnt lgkmcnt(14)
	v_mfma_f32_32x32x16_bf16 v[50:65], v[170:173], v[98:101], v[50:65]
	ds_read_b64_tr_b16 v[98:99], v243 offset:37888
	ds_read_b64_tr_b16 v[100:101], v243 offset:38400
	v_exp_f32_e32 v136, v136
	v_exp_f32_e32 v137, v137
	s_waitcnt lgkmcnt(14)
	v_mfma_f32_32x32x16_bf16 v[2:17], v[166:169], v[94:97], v[2:17]
	ds_read_b64_tr_b16 v[94:95], v243 offset:34816
	ds_read_b64_tr_b16 v[96:97], v243 offset:35328
	v_exp_f32_e32 v138, v138
	v_exp_f32_e32 v139, v139
	s_waitcnt lgkmcnt(12)
	v_mfma_f32_32x32x16_bf16 v[50:65], v[166:169], v[90:93], v[50:65]
	ds_read_b64_tr_b16 v[90:91], v243 offset:38912
	ds_read_b64_tr_b16 v[92:93], v243 offset:39424
	v_exp_f32_e32 v140, v140
	v_exp_f32_e32 v141, v141
	v_mfma_f32_32x32x16_bf16 v[2:17], v[162:165], v[86:89], v[2:17]
	ds_read_b64_tr_b16 v[86:87], v243 offset:35840
	ds_read_b64_tr_b16 v[88:89], v243 offset:36352
	v_exp_f32_e32 v142, v142
	v_exp_f32_e32 v143, v143
	s_waitcnt lgkmcnt(14)
	v_mfma_f32_32x32x16_bf16 v[50:65], v[162:165], v[82:85], v[50:65]
	ds_read_b64_tr_b16 v[244:245], v243 offset:39936
	ds_read_b64_tr_b16 v[246:247], v243 offset:40448
	v_exp_f32_e32 v144, v144
	v_exp_f32_e32 v145, v145
	s_waitcnt lgkmcnt(14)
; #define WAIT_BAR(N) asm volatile("s_waitcnt vmcnt(" #N ") lgkmcnt(0)\n\ts_barrier":::"memory")
;   #define RESC() do{ if(resc){ asm volatile("s_waitcnt lgkmcnt(0)":::"memory"); \
;       _Pragma("unroll") for(int d_=0;d_<2;++d_) _Pragma("unroll") for(int r=0;r<16;++r)o[d_][r]*=wsf[crow(r,hi)]; } }while(0)
;   #define ROT() do{sl_prev=sl_cur;sl_cur=sl_next;sl_next=(sl_next==(NSLOT-1)*SLOTB)?0:sl_next+SLOTB;}while(0)
;   #define RESC() do{ if(resc){ asm volatile("s_waitcnt lgkmcnt(0)":::"memory"); \
;       _Pragma("unroll") for(int d_=0;d_<4;++d_) _Pragma("unroll") for(int r=0;r<16;++r)o[d_][r]*=wsf[crow(r,hi)]; } }while(0)
;   #define ROT() do{sl_prev=sl_cur;sl_cur=sl_next;sl_next=(sl_next==(NSLOT-1)*SLOTB)?0:sl_next+SLOTB;}while(0)
; template<int THRL,int MODE> __device__ __forceinline__ void attn_unit128(const bf16*Qblk,const bf16*__restrict__ Kh,const bf16*__restrict__ Vh,bf16*Oblk,const int NT,char*shm,const bf16*O1blk,bf16*AOblk,const float lam,const float*sln,const float omli){
;     ...
;   int t=1;
;     ...
;   for(;t+5<NT;t+=2){
;     STEP(pB0,pB1,pA0,pA1,t,true,true,true);     WAIT_BAR(3); RESC(); ROT();
;     STEP(pA0,pA1,pB0,pB1,t+1,true,true,true);   WAIT_BAR(3); RESC(); ROT();
	v_mfma_f32_32x32x16_bf16 v[34:49], v[174:177], v[110:113], v[34:49]
	v_exp_f32_e32 v114, v114
	v_exp_f32_e32 v115, v115
	s_waitcnt lgkmcnt(12)
	v_mfma_f32_32x32x16_bf16 v[18:33], v[174:177], v[106:109], v[18:33]
	v_exp_f32_e32 v116, v116
	v_exp_f32_e32 v117, v117
	s_add_u32 s66, s100, s16
	s_addc_u32 s67, s101, s17
	s_add_u32 s66, s66, 0x120000
	s_addc_u32 s67, s67, 0
	s_add_i32 m0, s43, s22
	s_nop 0
	global_load_lds_dwordx4 v216, s[66:67]
	v_add_u32_e32 v106, s33, v240
	ds_read_b128 v[82:85], v106
	ds_read_b128 v[198:201], v106 offset:512
	s_waitcnt lgkmcnt(12)
	v_mfma_f32_32x32x16_bf16 v[34:49], v[170:173], v[102:105], v[34:49]
	v_exp_f32_e32 v118, v118
	v_exp_f32_e32 v119, v119
	ds_read_b128 v[202:205], v106 offset:2048
	ds_read_b128 v[194:197], v106 offset:2560
	s_waitcnt lgkmcnt(12)
	v_mfma_f32_32x32x16_bf16 v[18:33], v[170:173], v[98:101], v[18:33]
	v_exp_f32_e32 v120, v120
	v_exp_f32_e32 v121, v121
	ds_read_b128 v[158:161], v106 offset:4096
	ds_read_b128 v[154:157], v106 offset:4608
	s_waitcnt lgkmcnt(12)
	v_mfma_f32_32x32x16_bf16 v[34:49], v[166:169], v[94:97], v[34:49]
	v_exp_f32_e32 v122, v122
	v_exp_f32_e32 v123, v123
	ds_read_b128 v[150:153], v106 offset:6144
	ds_read_b128 v[146:149], v106 offset:6656
	s_waitcnt lgkmcnt(12)
	v_mfma_f32_32x32x16_bf16 v[18:33], v[166:169], v[90:93], v[18:33]
	v_exp_f32_e32 v124, v124
	v_exp_f32_e32 v125, v125
	s_waitcnt lgkmcnt(10)
	v_mfma_f32_32x32x16_bf16 v[34:49], v[162:165], v[86:89], v[34:49]
	v_exp_f32_e32 v126, v126
	v_exp_f32_e32 v127, v127
	s_add_u32 s66, s27, s16
	s_addc_u32 s67, s35, s17
	s_add_u32 s66, s66, 0x6290800
	s_addc_u32 s67, s67, 0
	s_add_i32 s20, s45, s24
	s_mov_b32 m0, s20
	s_nop 0
	global_load_lds_dwordx4 v0, s[66:67]
	s_waitcnt lgkmcnt(8)
	v_mfma_f32_32x32x16_bf16 v[18:33], v[162:165], v[244:247], v[18:33]
	v_exp_f32_e32 v128, v128
	v_exp_f32_e32 v129, v129
	s_addk_i32 s20, 0x1f80
	s_mov_b32 m0, s20
	s_nop 0
	global_load_lds_dwordx4 v0, s[66:67] offset:128
	s_waitcnt vmcnt(3) lgkmcnt(0)
	s_barrier
	s_andn2_b64 vcc, exec, s[18:19]
	s_cbranch_vccnz .LBB0_544
	s_waitcnt lgkmcnt(0)
	v_add_u32_e32 v98, s23, v241
	ds_read_b128 v[86:89], v98 offset:96
	ds_read_b128 v[90:93], v98 offset:64
	ds_read_b128 v[94:97], v98 offset:32
	ds_read_b128 v[98:101], v98
	s_waitcnt lgkmcnt(3)
	v_pk_mul_f32 v[14:15], v[14:15], v[86:87]
	s_waitcnt lgkmcnt(2)
	v_pk_mul_f32 v[10:11], v[10:11], v[90:91]
	s_waitcnt lgkmcnt(1)
	v_pk_mul_f32 v[6:7], v[6:7], v[94:95]
	v_pk_mul_f32 v[16:17], v[16:17], v[88:89]
	v_pk_mul_f32 v[12:13], v[12:13], v[92:93]
	v_pk_mul_f32 v[8:9], v[8:9], v[96:97]
	s_waitcnt lgkmcnt(0)
	v_pk_mul_f32 v[4:5], v[4:5], v[100:101]
	v_pk_mul_f32 v[2:3], v[2:3], v[98:99]
	v_pk_mul_f32 v[62:63], v[62:63], v[86:87]
	v_pk_mul_f32 v[58:59], v[58:59], v[90:91]
	v_pk_mul_f32 v[54:55], v[54:55], v[94:95]
	v_pk_mul_f32 v[64:65], v[64:65], v[88:89]
	v_pk_mul_f32 v[60:61], v[60:61], v[92:93]
	v_pk_mul_f32 v[56:57], v[56:57], v[96:97]
	v_pk_mul_f32 v[52:53], v[52:53], v[100:101]
	v_pk_mul_f32 v[50:51], v[50:51], v[98:99]
	v_pk_mul_f32 v[46:47], v[46:47], v[86:87]
	v_pk_mul_f32 v[42:43], v[42:43], v[90:91]
	v_pk_mul_f32 v[38:39], v[38:39], v[94:95]
	v_pk_mul_f32 v[48:49], v[48:49], v[88:89]
	v_pk_mul_f32 v[44:45], v[44:45], v[92:93]
	v_pk_mul_f32 v[40:41], v[40:41], v[96:97]
	v_pk_mul_f32 v[36:37], v[36:37], v[100:101]
	v_pk_mul_f32 v[34:35], v[34:35], v[98:99]
	v_pk_mul_f32 v[30:31], v[30:31], v[86:87]
	v_pk_mul_f32 v[26:27], v[26:27], v[90:91]
	v_pk_mul_f32 v[22:23], v[22:23], v[94:95]
	v_pk_mul_f32 v[32:33], v[32:33], v[88:89]
	v_pk_mul_f32 v[28:29], v[28:29], v[92:93]
	v_pk_mul_f32 v[24:25], v[24:25], v[96:97]
	v_pk_mul_f32 v[20:21], v[20:21], v[100:101]
	v_pk_mul_f32 v[18:19], v[18:19], v[98:99]
.LBB0_544:
	s_add_i32 s18, s33, 0x2000
	s_cmpk_lg_i32 s33, 0x4000
	s_cselect_b32 s46, s18, 0
	v_mfma_f32_32x32x16_bf16 v[98:113], v[82:85], v[190:193], v[66:81]
	v_add_f32_e32 v86, v130, v131
	v_add_f32_e32 v86, v132, v86
	v_add_f32_e32 v86, v133, v86
	s_lshl_b32 s18, s43, 1
	v_add_f32_e32 v86, v134, v86
	v_add_u32_e32 v243, s18, v238
	v_add_f32_e32 v82, v135, v86
	v_cvt_pk_bf16_f32 v174, v130, v131
	v_cvt_pk_bf16_f32 v175, v132, v133
	s_nop 0
	v_add_f32_e32 v82, v136, v82
	v_add_f32_e32 v82, v137, v82
	v_add_f32_e32 v82, v138, v82
	v_add_f32_e32 v130, v139, v82
	v_mfma_f32_32x32x16_bf16 v[82:97], v[198:201], v[190:193], v[66:81]
	v_cvt_pk_bf16_f32 v176, v134, v135
	v_cvt_pk_bf16_f32 v177, v136, v137
	v_mfma_f32_32x32x16_bf16 v[98:113], v[202:205], v[186:189], v[98:113]
	v_add_f32_e32 v130, v140, v130
	v_add_f32_e32 v130, v141, v130
	v_add_f32_e32 v130, v142, v130
	v_add_f32_e32 v130, v143, v130
	v_cvt_pk_bf16_f32 v170, v138, v139
	v_cvt_pk_bf16_f32 v171, v140, v141
	v_mfma_f32_32x32x16_bf16 v[82:97], v[194:197], v[186:189], v[82:97]
	v_add_f32_e32 v130, v144, v130
	v_add_f32_e32 v130, v145, v130
	v_add_f32_e32 v130, v114, v130
	v_add_f32_e32 v130, v115, v130
	v_cvt_pk_bf16_f32 v172, v142, v143
	v_cvt_pk_bf16_f32 v173, v144, v145
	v_mfma_f32_32x32x16_bf16 v[98:113], v[158:161], v[182:185], v[98:113]
	v_add_f32_e32 v130, v116, v130
	v_add_f32_e32 v130, v117, v130
	v_add_f32_e32 v130, v118, v130
	v_add_f32_e32 v130, v119, v130
	v_cvt_pk_bf16_f32 v166, v114, v115
	v_cvt_pk_bf16_f32 v167, v116, v117
	v_mfma_f32_32x32x16_bf16 v[82:97], v[154:157], v[182:185], v[82:97]
	v_add_f32_e32 v114, v120, v130
	v_add_f32_e32 v114, v121, v114
	v_add_f32_e32 v114, v122, v114
	v_add_f32_e32 v114, v123, v114
	v_cvt_pk_bf16_f32 v168, v118, v119
	v_cvt_pk_bf16_f32 v169, v120, v121
	v_mfma_f32_32x32x16_bf16 v[98:113], v[150:153], v[178:181], v[98:113]
	v_add_f32_e32 v114, v124, v114
	v_add_f32_e32 v114, v125, v114
	v_add_f32_e32 v114, v126, v114
	v_add_f32_e32 v114, v127, v114
	v_cvt_pk_bf16_f32 v162, v122, v123
	v_cvt_pk_bf16_f32 v163, v124, v125
	v_mfma_f32_32x32x16_bf16 v[82:97], v[146:149], v[178:181], v[82:97]
	v_add_f32_e32 v114, v128, v114
	v_add_f32_e32 v114, v129, v114
	v_add_f32_e32 v242, v242, v114
	v_cvt_pk_bf16_f32 v164, v126, v127
	v_cvt_pk_bf16_f32 v165, v128, v129
	ds_read_b64_tr_b16 v[142:143], v243 offset:24576
	ds_read_b64_tr_b16 v[144:145], v243 offset:25088
	ds_read_b64_tr_b16 v[134:135], v243 offset:25600
	ds_read_b64_tr_b16 v[136:137], v243 offset:26112
	ds_read_b64_tr_b16 v[138:139], v243 offset:28672
	ds_read_b64_tr_b16 v[140:141], v243 offset:29184
	ds_read_b64_tr_b16 v[130:131], v243 offset:29696
	ds_read_b64_tr_b16 v[132:133], v243 offset:30208
	ds_read_b64_tr_b16 v[126:127], v243 offset:26624
	ds_read_b64_tr_b16 v[128:129], v243 offset:27136
	ds_read_b64_tr_b16 v[118:119], v243 offset:27648
	ds_read_b64_tr_b16 v[120:121], v243 offset:28160
	ds_read_b64_tr_b16 v[122:123], v243 offset:30720
	ds_read_b64_tr_b16 v[124:125], v243 offset:31232
	ds_read_b64_tr_b16 v[114:115], v243 offset:31744
	ds_read_b64_tr_b16 v[116:117], v243 offset:32256
	s_add_u32 s18, s100, s16
	s_addc_u32 s19, s101, s17
	s_add_u32 s18, s18, 0x168000
	s_addc_u32 s19, s19, 0
	s_add_i32 m0, s33, s22
	s_nop 0
	global_load_lds_dwordx4 v216, s[18:19]
	s_lshl_b32 s43, s46, 1
	v_max3_f32 v146, v98, v99, v100
	v_max3_f32 v147, v101, v102, v103
	v_max3_f32 v146, v146, v104, v105
	v_max3_f32 v147, v147, v106, v107
	v_max3_f32 v146, v146, v108, v109
	v_max3_f32 v147, v147, v110, v111
	v_max3_f32 v146, v146, v112, v113
	v_max3_f32 v147, v147, v82, v83
	v_max3_f32 v146, v146, v84, v85
	v_max3_f32 v147, v147, v86, v87
	v_max3_f32 v146, v146, v88, v89
	v_max3_f32 v147, v147, v90, v91
	v_max3_f32 v146, v146, v92, v93
	v_max3_f32 v147, v147, v94, v95
	v_max3_f32 v146, v146, v96, v97
	v_max_f32_e32 v146, v146, v147
	v_mov_b32_e32 v147, v146
	s_nop 1
	v_permlane32_swap_b32_e32 v146, v147
	v_max_f32_e32 v146, v146, v147
	v_cmp_lt_f32_e32 vcc, s15, v146
	s_cmp_lg_u64 vcc, 0
	s_cselect_b64 s[18:19], -1, 0
	s_cbranch_vccnz .LBB0_552
; #define WAIT_BAR(N) asm volatile("s_waitcnt vmcnt(" #N ") lgkmcnt(0)\n\ts_barrier":::"memory")
;   #define RESC() do{ if(resc){ asm volatile("s_waitcnt lgkmcnt(0)":::"memory"); \
;       _Pragma("unroll") for(int d_=0;d_<2;++d_) _Pragma("unroll") for(int r=0;r<16;++r)o[d_][r]*=wsf[crow(r,hi)]; } }while(0)
;   #define ROT() do{sl_prev=sl_cur;sl_cur=sl_next;sl_next=(sl_next==(NSLOT-1)*SLOTB)?0:sl_next+SLOTB;}while(0)
;   #define RESC() do{ if(resc){ asm volatile("s_waitcnt lgkmcnt(0)":::"memory"); \
;       _Pragma("unroll") for(int d_=0;d_<4;++d_) _Pragma("unroll") for(int r=0;r<16;++r)o[d_][r]*=wsf[crow(r,hi)]; } }while(0)
;   #define ROT() do{sl_prev=sl_cur;sl_cur=sl_next;sl_next=(sl_next==(NSLOT-1)*SLOTB)?0:sl_next+SLOTB;}while(0)
; template<int THRL,int MODE> __device__ __forceinline__ void attn_unit128(const bf16*Qblk,const bf16*__restrict__ Kh,const bf16*__restrict__ Vh,bf16*Oblk,const int NT,char*shm,const bf16*O1blk,bf16*AOblk,const float lam,const float*sln,const float omli){
;     ...
;   int t=1;
;     ...
;   for(;t+5<NT;t+=2){
;     STEP(pB0,pB1,pA0,pA1,t,true,true,true);     WAIT_BAR(3); RESC(); ROT();
;     STEP(pA0,pA1,pB0,pB1,t+1,true,true,true);   WAIT_BAR(3); RESC(); ROT();
.LBB0_545:
	s_waitcnt lgkmcnt(14)
	v_mfma_f32_32x32x16_bf16 v[2:17], v[174:177], v[142:145], v[2:17]
	ds_read_b64_tr_b16 v[142:143], v243 offset:32768
	ds_read_b64_tr_b16 v[144:145], v243 offset:33280
	v_exp_f32_e32 v98, v98
	v_exp_f32_e32 v99, v99
	s_waitcnt lgkmcnt(12)
	v_mfma_f32_32x32x16_bf16 v[50:65], v[174:177], v[138:141], v[50:65]
	ds_read_b64_tr_b16 v[138:139], v243 offset:36864
	ds_read_b64_tr_b16 v[140:141], v243 offset:37376
	v_exp_f32_e32 v100, v100
	v_exp_f32_e32 v101, v101
	v_mfma_f32_32x32x16_bf16 v[2:17], v[170:173], v[134:137], v[2:17]
	ds_read_b64_tr_b16 v[134:135], v243 offset:33792
	ds_read_b64_tr_b16 v[136:137], v243 offset:34304
	v_exp_f32_e32 v102, v102
	v_exp_f32_e32 v103, v103
	s_waitcnt lgkmcnt(14)
	v_mfma_f32_32x32x16_bf16 v[50:65], v[170:173], v[130:133], v[50:65]
	ds_read_b64_tr_b16 v[130:131], v243 offset:37888
	ds_read_b64_tr_b16 v[132:133], v243 offset:38400
	v_exp_f32_e32 v104, v104
	v_exp_f32_e32 v105, v105
	s_waitcnt lgkmcnt(14)
	v_mfma_f32_32x32x16_bf16 v[2:17], v[166:169], v[126:129], v[2:17]
	ds_read_b64_tr_b16 v[126:127], v243 offset:34816
	ds_read_b64_tr_b16 v[128:129], v243 offset:35328
	v_exp_f32_e32 v106, v106
	v_exp_f32_e32 v107, v107
	s_waitcnt lgkmcnt(12)
	v_mfma_f32_32x32x16_bf16 v[50:65], v[166:169], v[122:125], v[50:65]
	ds_read_b64_tr_b16 v[122:123], v243 offset:38912
	ds_read_b64_tr_b16 v[124:125], v243 offset:39424
	v_exp_f32_e32 v108, v108
	v_exp_f32_e32 v109, v109
	v_mfma_f32_32x32x16_bf16 v[2:17], v[162:165], v[118:121], v[2:17]
	ds_read_b64_tr_b16 v[118:119], v243 offset:35840
	ds_read_b64_tr_b16 v[120:121], v243 offset:36352
	v_exp_f32_e32 v110, v110
	v_exp_f32_e32 v111, v111
	s_waitcnt lgkmcnt(14)
	v_mfma_f32_32x32x16_bf16 v[50:65], v[162:165], v[114:117], v[50:65]
	ds_read_b64_tr_b16 v[214:215], v243 offset:39936
	ds_read_b64_tr_b16 v[216:217], v243 offset:40448
	v_exp_f32_e32 v112, v112
	v_exp_f32_e32 v113, v113
	s_waitcnt lgkmcnt(14)
	v_mfma_f32_32x32x16_bf16 v[34:49], v[174:177], v[142:145], v[34:49]
	v_exp_f32_e32 v82, v82
	v_exp_f32_e32 v83, v83
	s_waitcnt lgkmcnt(12)
	v_mfma_f32_32x32x16_bf16 v[18:33], v[174:177], v[138:141], v[18:33]
	v_exp_f32_e32 v84, v84
	v_exp_f32_e32 v85, v85
	v_add_u32_e32 v138, s46, v240
	ds_read_b128 v[114:117], v138
	ds_read_b128 v[198:201], v138 offset:512
	s_waitcnt lgkmcnt(12)
	v_mfma_f32_32x32x16_bf16 v[34:49], v[170:173], v[134:137], v[34:49]
	v_exp_f32_e32 v86, v86
	v_exp_f32_e32 v87, v87
	ds_read_b128 v[202:205], v138 offset:2048
	ds_read_b128 v[194:197], v138 offset:2560
	s_waitcnt lgkmcnt(12)
	v_mfma_f32_32x32x16_bf16 v[18:33], v[170:173], v[130:133], v[18:33]
	v_exp_f32_e32 v88, v88
	v_exp_f32_e32 v89, v89
	ds_read_b128 v[158:161], v138 offset:4096
	ds_read_b128 v[154:157], v138 offset:4608
	s_waitcnt lgkmcnt(12)
	v_mfma_f32_32x32x16_bf16 v[34:49], v[166:169], v[126:129], v[34:49]
	v_exp_f32_e32 v90, v90
	v_exp_f32_e32 v91, v91
	ds_read_b128 v[150:153], v138 offset:6144
	ds_read_b128 v[146:149], v138 offset:6656
	s_waitcnt lgkmcnt(12)
	v_mfma_f32_32x32x16_bf16 v[18:33], v[166:169], v[122:125], v[18:33]
	v_exp_f32_e32 v92, v92
	v_exp_f32_e32 v93, v93
	s_waitcnt lgkmcnt(10)
	v_mfma_f32_32x32x16_bf16 v[34:49], v[162:165], v[118:121], v[34:49]
	v_exp_f32_e32 v94, v94
	v_exp_f32_e32 v95, v95
	s_add_u32 s66, s27, s16
	s_addc_u32 s67, s35, s17
	s_add_u32 s66, s66, 0x62d8800
	s_addc_u32 s67, s67, 0
	s_add_i32 s20, s43, s24
	s_mov_b32 m0, s20
	s_nop 0
	global_load_lds_dwordx4 v0, s[66:67]
	s_waitcnt lgkmcnt(8)
	v_mfma_f32_32x32x16_bf16 v[18:33], v[162:165], v[214:217], v[18:33]
	v_exp_f32_e32 v96, v96
	v_exp_f32_e32 v97, v97
	s_addk_i32 s20, 0x1f80
	s_mov_b32 m0, s20
	s_nop 0
	global_load_lds_dwordx4 v0, s[66:67] offset:128
	s_waitcnt vmcnt(3) lgkmcnt(0)
	s_barrier
	s_andn2_b64 vcc, exec, s[18:19]
	s_cbranch_vccnz .LBB0_547
	s_waitcnt lgkmcnt(0)
	v_add_u32_e32 v130, s23, v241
	ds_read_b128 v[118:121], v130 offset:96
	ds_read_b128 v[122:125], v130 offset:64
	ds_read_b128 v[126:129], v130 offset:32
	ds_read_b128 v[130:133], v130
	s_waitcnt lgkmcnt(3)
	v_pk_mul_f32 v[14:15], v[14:15], v[118:119]
	s_waitcnt lgkmcnt(2)
	v_pk_mul_f32 v[10:11], v[10:11], v[122:123]
	s_waitcnt lgkmcnt(1)
	v_pk_mul_f32 v[6:7], v[6:7], v[126:127]
	v_pk_mul_f32 v[16:17], v[16:17], v[120:121]
	v_pk_mul_f32 v[12:13], v[12:13], v[124:125]
	v_pk_mul_f32 v[8:9], v[8:9], v[128:129]
	s_waitcnt lgkmcnt(0)
	v_pk_mul_f32 v[4:5], v[4:5], v[132:133]
	v_pk_mul_f32 v[2:3], v[2:3], v[130:131]
	v_pk_mul_f32 v[62:63], v[62:63], v[118:119]
	v_pk_mul_f32 v[58:59], v[58:59], v[122:123]
	v_pk_mul_f32 v[54:55], v[54:55], v[126:127]
	v_pk_mul_f32 v[64:65], v[64:65], v[120:121]
	v_pk_mul_f32 v[60:61], v[60:61], v[124:125]
	v_pk_mul_f32 v[56:57], v[56:57], v[128:129]
	v_pk_mul_f32 v[52:53], v[52:53], v[132:133]
	v_pk_mul_f32 v[50:51], v[50:51], v[130:131]
	v_pk_mul_f32 v[46:47], v[46:47], v[118:119]
	v_pk_mul_f32 v[42:43], v[42:43], v[122:123]
	v_pk_mul_f32 v[38:39], v[38:39], v[126:127]
	v_pk_mul_f32 v[48:49], v[48:49], v[120:121]
	v_pk_mul_f32 v[44:45], v[44:45], v[124:125]
	v_pk_mul_f32 v[40:41], v[40:41], v[128:129]
	v_pk_mul_f32 v[36:37], v[36:37], v[132:133]
	v_pk_mul_f32 v[34:35], v[34:35], v[130:131]
	v_pk_mul_f32 v[30:31], v[30:31], v[118:119]
	v_pk_mul_f32 v[26:27], v[26:27], v[122:123]
	v_pk_mul_f32 v[22:23], v[22:23], v[126:127]
	v_pk_mul_f32 v[32:33], v[32:33], v[120:121]
	v_pk_mul_f32 v[28:29], v[28:29], v[124:125]
	v_pk_mul_f32 v[24:25], v[24:25], v[128:129]
	v_pk_mul_f32 v[20:21], v[20:21], v[132:133]
	v_pk_mul_f32 v[18:19], v[18:19], v[130:131]

.LBB0_573:
	v_mfma_f32_32x32x16_bf16 v[130:145], v[114:117], v[190:193], v[66:81]
	v_add_f32_e32 v118, v98, v99
	v_add_f32_e32 v118, v100, v118
	v_add_f32_e32 v118, v101, v118
	s_lshl_b32 s6, s6, 1
	v_add_f32_e32 v118, v102, v118
	v_add_u32_e32 v243, s6, v238
	v_add_f32_e32 v114, v103, v118
	v_cvt_pk_bf16_f32 v174, v98, v99
	v_cvt_pk_bf16_f32 v175, v100, v101
	s_nop 0
	v_add_f32_e32 v98, v104, v114
	v_mfma_f32_32x32x16_bf16 v[114:129], v[198:201], v[190:193], v[66:81]
	v_add_f32_e32 v98, v105, v98
	v_add_f32_e32 v98, v106, v98
	v_add_f32_e32 v98, v107, v98
	v_cvt_pk_bf16_f32 v176, v102, v103
	v_cvt_pk_bf16_f32 v177, v104, v105
	v_mfma_f32_32x32x16_bf16 v[130:145], v[202:205], v[186:189], v[130:145]
	v_add_f32_e32 v98, v108, v98
	v_add_f32_e32 v98, v109, v98
	v_add_f32_e32 v98, v110, v98
	v_add_f32_e32 v98, v111, v98
	v_cvt_pk_bf16_f32 v170, v106, v107
	v_cvt_pk_bf16_f32 v171, v108, v109
	v_mfma_f32_32x32x16_bf16 v[114:129], v[194:197], v[186:189], v[114:129]
	v_add_f32_e32 v98, v112, v98
	v_add_f32_e32 v98, v113, v98
	v_add_f32_e32 v98, v82, v98
	v_add_f32_e32 v98, v83, v98
	v_cvt_pk_bf16_f32 v172, v110, v111
	v_cvt_pk_bf16_f32 v173, v112, v113
	v_mfma_f32_32x32x16_bf16 v[130:145], v[158:161], v[182:185], v[130:145]
	v_add_f32_e32 v98, v84, v98
	v_add_f32_e32 v98, v85, v98
	v_add_f32_e32 v98, v86, v98
	v_add_f32_e32 v98, v87, v98
	v_cvt_pk_bf16_f32 v166, v82, v83
	v_cvt_pk_bf16_f32 v167, v84, v85
	v_mfma_f32_32x32x16_bf16 v[114:129], v[154:157], v[182:185], v[114:129]
	v_add_f32_e32 v82, v88, v98
	v_add_f32_e32 v82, v89, v82
	v_add_f32_e32 v82, v90, v82
	v_add_f32_e32 v82, v91, v82
	v_cvt_pk_bf16_f32 v168, v86, v87
	v_cvt_pk_bf16_f32 v169, v88, v89
	v_mfma_f32_32x32x16_bf16 v[130:145], v[150:153], v[178:181], v[130:145]
	v_add_f32_e32 v82, v92, v82
	v_add_f32_e32 v82, v93, v82
	v_add_f32_e32 v82, v94, v82
	v_add_f32_e32 v82, v95, v82
	v_cvt_pk_bf16_f32 v162, v90, v91
	v_cvt_pk_bf16_f32 v163, v92, v93
	v_mfma_f32_32x32x16_bf16 v[114:129], v[146:149], v[178:181], v[114:129]
	v_add_f32_e32 v82, v96, v82
	v_add_f32_e32 v82, v97, v82
	v_add_f32_e32 v242, v242, v82
	v_cvt_pk_bf16_f32 v164, v94, v95
	v_cvt_pk_bf16_f32 v165, v96, v97
	ds_read_b64_tr_b16 v[110:111], v243 offset:24576
	ds_read_b64_tr_b16 v[112:113], v243 offset:25088
	ds_read_b64_tr_b16 v[102:103], v243 offset:25600
	ds_read_b64_tr_b16 v[104:105], v243 offset:26112
	ds_read_b64_tr_b16 v[106:107], v243 offset:28672
	ds_read_b64_tr_b16 v[108:109], v243 offset:29184
	ds_read_b64_tr_b16 v[98:99], v243 offset:29696
	ds_read_b64_tr_b16 v[100:101], v243 offset:30208
	ds_read_b64_tr_b16 v[94:95], v243 offset:26624
	ds_read_b64_tr_b16 v[96:97], v243 offset:27136
	ds_read_b64_tr_b16 v[86:87], v243 offset:27648
	ds_read_b64_tr_b16 v[88:89], v243 offset:28160
	ds_read_b64_tr_b16 v[90:91], v243 offset:30720
	ds_read_b64_tr_b16 v[92:93], v243 offset:31232
	ds_read_b64_tr_b16 v[82:83], v243 offset:31744
	ds_read_b64_tr_b16 v[84:85], v243 offset:32256
	v_subrev_u32_e32 v216, s100, v212
	s_lshl_b32 s11, s45, 1
	v_max3_f32 v146, v130, v131, v132
	v_max3_f32 v147, v133, v134, v135
	v_max3_f32 v146, v146, v136, v137
	v_max3_f32 v147, v147, v138, v139
	v_max3_f32 v146, v146, v140, v141
	v_max3_f32 v147, v147, v142, v143
	v_max3_f32 v146, v146, v144, v145
	v_max3_f32 v147, v147, v114, v115
	v_max3_f32 v146, v146, v116, v117
	v_max3_f32 v147, v147, v118, v119
	v_max3_f32 v146, v146, v120, v121
	v_max3_f32 v147, v147, v122, v123
	v_max3_f32 v146, v146, v124, v125
	v_max3_f32 v147, v147, v126, v127
	v_max3_f32 v146, v146, v128, v129
	v_max_f32_e32 v146, v146, v147
	v_mov_b32_e32 v147, v146
	s_nop 1
	v_permlane32_swap_b32_e32 v146, v147
	v_max_f32_e32 v146, v146, v147
	v_cmp_lt_f32_e32 vcc, s15, v146
	s_cmp_lg_u64 vcc, 0
	s_cselect_b64 s[6:7], -1, 0
	s_cbranch_vccnz .LBB0_581
.LBB0_574:
	s_waitcnt lgkmcnt(14)
	v_mfma_f32_32x32x16_bf16 v[2:17], v[174:177], v[110:113], v[2:17]
	ds_read_b64_tr_b16 v[110:111], v243 offset:32768
	ds_read_b64_tr_b16 v[112:113], v243 offset:33280
	v_exp_f32_e32 v130, v130
	v_exp_f32_e32 v131, v131
	s_waitcnt lgkmcnt(12)
	v_mfma_f32_32x32x16_bf16 v[50:65], v[174:177], v[106:109], v[50:65]
	ds_read_b64_tr_b16 v[106:107], v243 offset:36864
	ds_read_b64_tr_b16 v[108:109], v243 offset:37376
	v_exp_f32_e32 v132, v132
	v_exp_f32_e32 v133, v133
	v_mfma_f32_32x32x16_bf16 v[2:17], v[170:173], v[102:105], v[2:17]
	ds_read_b64_tr_b16 v[102:103], v243 offset:33792
	ds_read_b64_tr_b16 v[104:105], v243 offset:34304
	v_exp_f32_e32 v134, v134
	v_exp_f32_e32 v135, v135
	s_waitcnt lgkmcnt(14)
	v_mfma_f32_32x32x16_bf16 v[50:65], v[170:173], v[98:101], v[50:65]
	ds_read_b64_tr_b16 v[98:99], v243 offset:37888
	ds_read_b64_tr_b16 v[100:101], v243 offset:38400
	v_exp_f32_e32 v136, v136
	v_exp_f32_e32 v137, v137
	s_waitcnt lgkmcnt(14)
	v_mfma_f32_32x32x16_bf16 v[2:17], v[166:169], v[94:97], v[2:17]
	ds_read_b64_tr_b16 v[94:95], v243 offset:34816
	ds_read_b64_tr_b16 v[96:97], v243 offset:35328
	v_exp_f32_e32 v138, v138
	v_exp_f32_e32 v139, v139
	s_waitcnt lgkmcnt(12)
	v_mfma_f32_32x32x16_bf16 v[50:65], v[166:169], v[90:93], v[50:65]
	ds_read_b64_tr_b16 v[90:91], v243 offset:38912
	ds_read_b64_tr_b16 v[92:93], v243 offset:39424
	v_exp_f32_e32 v140, v140
	v_exp_f32_e32 v141, v141
	v_mfma_f32_32x32x16_bf16 v[2:17], v[162:165], v[86:89], v[2:17]
	ds_read_b64_tr_b16 v[86:87], v243 offset:35840
	ds_read_b64_tr_b16 v[88:89], v243 offset:36352
	v_exp_f32_e32 v142, v142
	v_exp_f32_e32 v143, v143
	s_waitcnt lgkmcnt(14)
	v_mfma_f32_32x32x16_bf16 v[50:65], v[162:165], v[82:85], v[50:65]
	ds_read_b64_tr_b16 v[244:245], v243 offset:39936
	ds_read_b64_tr_b16 v[246:247], v243 offset:40448
	v_exp_f32_e32 v144, v144
	v_exp_f32_e32 v145, v145
	s_waitcnt lgkmcnt(14)
; #define WAIT_BAR(N) asm volatile("s_waitcnt vmcnt(" #N ") lgkmcnt(0)\n\ts_barrier":::"memory")
;   #define RESC() do{ if(resc){ asm volatile("s_waitcnt lgkmcnt(0)":::"memory"); \
;       _Pragma("unroll") for(int d_=0;d_<2;++d_) _Pragma("unroll") for(int r=0;r<16;++r)o[d_][r]*=wsf[crow(r,hi)]; } }while(0)
;   #define ROT() do{sl_prev=sl_cur;sl_cur=sl_next;sl_next=(sl_next==(NSLOT-1)*SLOTB)?0:sl_next+SLOTB;}while(0)
;   #define RESC() do{ if(resc){ asm volatile("s_waitcnt lgkmcnt(0)":::"memory"); \
;       _Pragma("unroll") for(int d_=0;d_<4;++d_) _Pragma("unroll") for(int r=0;r<16;++r)o[d_][r]*=wsf[crow(r,hi)]; } }while(0)
;   #define ROT() do{sl_prev=sl_cur;sl_cur=sl_next;sl_next=(sl_next==(NSLOT-1)*SLOTB)?0:sl_next+SLOTB;}while(0)
; template<int THRL,int MODE> __device__ __forceinline__ void attn_unit128(const bf16*Qblk,const bf16*__restrict__ Kh,const bf16*__restrict__ Vh,bf16*Oblk,const int NT,char*shm,const bf16*O1blk,bf16*AOblk,const float lam,const float*sln,const float omli){
;     ...
;   int t=1;
;     ...
;   for(;t+5<NT;t+=2){
;     STEP(pB0,pB1,pA0,pA1,t,true,true,true);     WAIT_BAR(3); RESC(); ROT();
;     STEP(pA0,pA1,pB0,pB1,t+1,true,true,true);   WAIT_BAR(3); RESC(); ROT();
	v_mfma_f32_32x32x16_bf16 v[34:49], v[174:177], v[110:113], v[34:49]
	v_exp_f32_e32 v114, v114
	v_exp_f32_e32 v115, v115
	s_waitcnt lgkmcnt(12)
	v_mfma_f32_32x32x16_bf16 v[18:33], v[174:177], v[106:109], v[18:33]
	v_exp_f32_e32 v116, v116
	v_exp_f32_e32 v117, v117
	s_add_u32 s66, s100, s4
	s_addc_u32 s67, s101, s5
	s_add_u32 s66, s66, 0x120000
	s_addc_u32 s67, s67, 0
	s_add_i32 m0, s56, s33
	s_nop 0
	global_load_lds_dwordx4 v216, s[66:67]
	v_add_u32_e32 v106, s45, v240
	ds_read_b128 v[82:85], v106
	ds_read_b128 v[198:201], v106 offset:512
	s_waitcnt lgkmcnt(12)
	v_mfma_f32_32x32x16_bf16 v[34:49], v[170:173], v[102:105], v[34:49]
	v_exp_f32_e32 v118, v118
	v_exp_f32_e32 v119, v119
	ds_read_b128 v[202:205], v106 offset:2048
	ds_read_b128 v[194:197], v106 offset:2560
	s_waitcnt lgkmcnt(12)
	v_mfma_f32_32x32x16_bf16 v[18:33], v[170:173], v[98:101], v[18:33]
	v_exp_f32_e32 v120, v120
	v_exp_f32_e32 v121, v121
	ds_read_b128 v[158:161], v106 offset:4096
	ds_read_b128 v[154:157], v106 offset:4608
	s_waitcnt lgkmcnt(12)
	v_mfma_f32_32x32x16_bf16 v[34:49], v[166:169], v[94:97], v[34:49]
	v_exp_f32_e32 v122, v122
	v_exp_f32_e32 v123, v123
	ds_read_b128 v[150:153], v106 offset:6144
	ds_read_b128 v[146:149], v106 offset:6656
	s_waitcnt lgkmcnt(12)
	v_mfma_f32_32x32x16_bf16 v[18:33], v[166:169], v[90:93], v[18:33]
	v_exp_f32_e32 v124, v124
	v_exp_f32_e32 v125, v125
	s_waitcnt lgkmcnt(10)
	v_mfma_f32_32x32x16_bf16 v[34:49], v[162:165], v[86:89], v[34:49]
	v_exp_f32_e32 v126, v126
	v_exp_f32_e32 v127, v127
	s_add_u32 s66, s27, s4
	s_addc_u32 s67, s35, s5
	s_add_u32 s66, s66, 0x6290800
	s_addc_u32 s67, s67, 0
	s_add_i32 s8, s11, s28
	s_mov_b32 m0, s8
	s_nop 0
	global_load_lds_dwordx4 v0, s[66:67]
	s_waitcnt lgkmcnt(8)
	v_mfma_f32_32x32x16_bf16 v[18:33], v[162:165], v[244:247], v[18:33]
	v_exp_f32_e32 v128, v128
	v_exp_f32_e32 v129, v129
	s_addk_i32 s8, 0x1f80
	s_mov_b32 m0, s8
	s_nop 0
	global_load_lds_dwordx4 v0, s[66:67] offset:128
	s_waitcnt vmcnt(3) lgkmcnt(0)
	s_barrier
	s_andn2_b64 vcc, exec, s[6:7]
	s_cbranch_vccnz .LBB0_576
	s_waitcnt lgkmcnt(0)
	v_add_u32_e32 v98, s36, v241
	ds_read_b128 v[86:89], v98 offset:96
	ds_read_b128 v[90:93], v98 offset:64
	ds_read_b128 v[94:97], v98 offset:32
	ds_read_b128 v[98:101], v98
	s_waitcnt lgkmcnt(3)
	v_pk_mul_f32 v[14:15], v[14:15], v[86:87]
	s_waitcnt lgkmcnt(2)
	v_pk_mul_f32 v[10:11], v[10:11], v[90:91]
	s_waitcnt lgkmcnt(1)
	v_pk_mul_f32 v[6:7], v[6:7], v[94:95]
	v_pk_mul_f32 v[16:17], v[16:17], v[88:89]
	v_pk_mul_f32 v[12:13], v[12:13], v[92:93]
	v_pk_mul_f32 v[8:9], v[8:9], v[96:97]
	s_waitcnt lgkmcnt(0)
	v_pk_mul_f32 v[4:5], v[4:5], v[100:101]
	v_pk_mul_f32 v[2:3], v[2:3], v[98:99]
	v_pk_mul_f32 v[62:63], v[62:63], v[86:87]
	v_pk_mul_f32 v[58:59], v[58:59], v[90:91]
	v_pk_mul_f32 v[54:55], v[54:55], v[94:95]
	v_pk_mul_f32 v[64:65], v[64:65], v[88:89]
	v_pk_mul_f32 v[60:61], v[60:61], v[92:93]
	v_pk_mul_f32 v[56:57], v[56:57], v[96:97]
	v_pk_mul_f32 v[52:53], v[52:53], v[100:101]
	v_pk_mul_f32 v[50:51], v[50:51], v[98:99]
	v_pk_mul_f32 v[46:47], v[46:47], v[86:87]
	v_pk_mul_f32 v[42:43], v[42:43], v[90:91]
	v_pk_mul_f32 v[38:39], v[38:39], v[94:95]
	v_pk_mul_f32 v[48:49], v[48:49], v[88:89]
	v_pk_mul_f32 v[44:45], v[44:45], v[92:93]
	v_pk_mul_f32 v[40:41], v[40:41], v[96:97]
	v_pk_mul_f32 v[36:37], v[36:37], v[100:101]
	v_pk_mul_f32 v[34:35], v[34:35], v[98:99]
	v_pk_mul_f32 v[30:31], v[30:31], v[86:87]
	v_pk_mul_f32 v[26:27], v[26:27], v[90:91]
	v_pk_mul_f32 v[22:23], v[22:23], v[94:95]
	v_pk_mul_f32 v[32:33], v[32:33], v[88:89]
	v_pk_mul_f32 v[28:29], v[28:29], v[92:93]
	v_pk_mul_f32 v[24:25], v[24:25], v[96:97]
	v_pk_mul_f32 v[20:21], v[20:21], v[100:101]
	v_pk_mul_f32 v[18:19], v[18:19], v[98:99]
.LBB0_576:
	s_add_i32 s6, s45, 0x2000
	s_cmpk_lg_i32 s45, 0x4000
	s_cselect_b32 s57, s6, 0
	v_mfma_f32_32x32x16_bf16 v[98:113], v[82:85], v[190:193], v[66:81]
	v_add_f32_e32 v86, v130, v131
	v_add_f32_e32 v86, v132, v86
	v_add_f32_e32 v86, v133, v86
	s_lshl_b32 s6, s56, 1
	v_add_f32_e32 v86, v134, v86
	v_add_u32_e32 v243, s6, v238
	v_add_f32_e32 v82, v135, v86
	v_cvt_pk_bf16_f32 v174, v130, v131
	v_cvt_pk_bf16_f32 v175, v132, v133
	s_nop 0
	v_add_f32_e32 v82, v136, v82
	v_add_f32_e32 v82, v137, v82
	v_add_f32_e32 v82, v138, v82
	v_add_f32_e32 v130, v139, v82
	v_mfma_f32_32x32x16_bf16 v[82:97], v[198:201], v[190:193], v[66:81]
	v_cvt_pk_bf16_f32 v176, v134, v135
	v_cvt_pk_bf16_f32 v177, v136, v137
	v_mfma_f32_32x32x16_bf16 v[98:113], v[202:205], v[186:189], v[98:113]
	v_add_f32_e32 v130, v140, v130
	v_add_f32_e32 v130, v141, v130
	v_add_f32_e32 v130, v142, v130
	v_add_f32_e32 v130, v143, v130
	v_cvt_pk_bf16_f32 v170, v138, v139
	v_cvt_pk_bf16_f32 v171, v140, v141
	v_mfma_f32_32x32x16_bf16 v[82:97], v[194:197], v[186:189], v[82:97]
	v_add_f32_e32 v130, v144, v130
	v_add_f32_e32 v130, v145, v130
	v_add_f32_e32 v130, v114, v130
	v_add_f32_e32 v130, v115, v130
	v_cvt_pk_bf16_f32 v172, v142, v143
	v_cvt_pk_bf16_f32 v173, v144, v145
	v_mfma_f32_32x32x16_bf16 v[98:113], v[158:161], v[182:185], v[98:113]
	v_add_f32_e32 v130, v116, v130
	v_add_f32_e32 v130, v117, v130
	v_add_f32_e32 v130, v118, v130
	v_add_f32_e32 v130, v119, v130
	v_cvt_pk_bf16_f32 v166, v114, v115
	v_cvt_pk_bf16_f32 v167, v116, v117
	v_mfma_f32_32x32x16_bf16 v[82:97], v[154:157], v[182:185], v[82:97]
	v_add_f32_e32 v114, v120, v130
	v_add_f32_e32 v114, v121, v114
	v_add_f32_e32 v114, v122, v114
	v_add_f32_e32 v114, v123, v114
	v_cvt_pk_bf16_f32 v168, v118, v119
	v_cvt_pk_bf16_f32 v169, v120, v121
	v_mfma_f32_32x32x16_bf16 v[98:113], v[150:153], v[178:181], v[98:113]
	v_add_f32_e32 v114, v124, v114
	v_add_f32_e32 v114, v125, v114
	v_add_f32_e32 v114, v126, v114
	v_add_f32_e32 v114, v127, v114
	v_cvt_pk_bf16_f32 v162, v122, v123
	v_cvt_pk_bf16_f32 v163, v124, v125
	v_mfma_f32_32x32x16_bf16 v[82:97], v[146:149], v[178:181], v[82:97]
	v_add_f32_e32 v114, v128, v114
	v_add_f32_e32 v114, v129, v114
	v_add_f32_e32 v242, v242, v114
	v_cvt_pk_bf16_f32 v164, v126, v127
	v_cvt_pk_bf16_f32 v165, v128, v129
	ds_read_b64_tr_b16 v[142:143], v243 offset:24576
	ds_read_b64_tr_b16 v[144:145], v243 offset:25088
	ds_read_b64_tr_b16 v[134:135], v243 offset:25600
	ds_read_b64_tr_b16 v[136:137], v243 offset:26112
	ds_read_b64_tr_b16 v[138:139], v243 offset:28672
	ds_read_b64_tr_b16 v[140:141], v243 offset:29184
	ds_read_b64_tr_b16 v[130:131], v243 offset:29696
	ds_read_b64_tr_b16 v[132:133], v243 offset:30208
	ds_read_b64_tr_b16 v[126:127], v243 offset:26624
	ds_read_b64_tr_b16 v[128:129], v243 offset:27136
	ds_read_b64_tr_b16 v[118:119], v243 offset:27648
	ds_read_b64_tr_b16 v[120:121], v243 offset:28160
	ds_read_b64_tr_b16 v[122:123], v243 offset:30720
	ds_read_b64_tr_b16 v[124:125], v243 offset:31232
	ds_read_b64_tr_b16 v[114:115], v243 offset:31744
	ds_read_b64_tr_b16 v[116:117], v243 offset:32256
	s_add_u32 s6, s100, s4
	s_addc_u32 s7, s101, s5
	s_add_u32 s6, s6, 0x168000
	s_addc_u32 s7, s7, 0
	s_add_i32 m0, s45, s33
	s_nop 0
	global_load_lds_dwordx4 v216, s[6:7]
	s_lshl_b32 s10, s57, 1
	v_max3_f32 v146, v98, v99, v100
	v_max3_f32 v147, v101, v102, v103
	v_max3_f32 v146, v146, v104, v105
	v_max3_f32 v147, v147, v106, v107
	v_max3_f32 v146, v146, v108, v109
	v_max3_f32 v147, v147, v110, v111
	v_max3_f32 v146, v146, v112, v113
	v_max3_f32 v147, v147, v82, v83
	v_max3_f32 v146, v146, v84, v85
	v_max3_f32 v147, v147, v86, v87
	v_max3_f32 v146, v146, v88, v89
	v_max3_f32 v147, v147, v90, v91
	v_max3_f32 v146, v146, v92, v93
	v_max3_f32 v147, v147, v94, v95
	v_max3_f32 v146, v146, v96, v97
	v_max_f32_e32 v146, v146, v147
	v_mov_b32_e32 v147, v146
	s_nop 1
	v_permlane32_swap_b32_e32 v146, v147
	v_max_f32_e32 v146, v146, v147
	v_cmp_lt_f32_e32 vcc, s15, v146
	s_cmp_lg_u64 vcc, 0
	s_cselect_b64 s[6:7], -1, 0
	s_cbranch_vccnz .LBB0_584
; #define WAIT_BAR(N) asm volatile("s_waitcnt vmcnt(" #N ") lgkmcnt(0)\n\ts_barrier":::"memory")
;   #define RESC() do{ if(resc){ asm volatile("s_waitcnt lgkmcnt(0)":::"memory"); \
;       _Pragma("unroll") for(int d_=0;d_<2;++d_) _Pragma("unroll") for(int r=0;r<16;++r)o[d_][r]*=wsf[crow(r,hi)]; } }while(0)
;   #define ROT() do{sl_prev=sl_cur;sl_cur=sl_next;sl_next=(sl_next==(NSLOT-1)*SLOTB)?0:sl_next+SLOTB;}while(0)
;   #define RESC() do{ if(resc){ asm volatile("s_waitcnt lgkmcnt(0)":::"memory"); \
;       _Pragma("unroll") for(int d_=0;d_<4;++d_) _Pragma("unroll") for(int r=0;r<16;++r)o[d_][r]*=wsf[crow(r,hi)]; } }while(0)
;   #define ROT() do{sl_prev=sl_cur;sl_cur=sl_next;sl_next=(sl_next==(NSLOT-1)*SLOTB)?0:sl_next+SLOTB;}while(0)
; template<int THRL,int MODE> __device__ __forceinline__ void attn_unit128(const bf16*Qblk,const bf16*__restrict__ Kh,const bf16*__restrict__ Vh,bf16*Oblk,const int NT,char*shm,const bf16*O1blk,bf16*AOblk,const float lam,const float*sln,const float omli){
;     ...
;   int t=1;
;     ...
;   for(;t+5<NT;t+=2){
;     STEP(pB0,pB1,pA0,pA1,t,true,true,true);     WAIT_BAR(3); RESC(); ROT();
;     STEP(pA0,pA1,pB0,pB1,t+1,true,true,true);   WAIT_BAR(3); RESC(); ROT();
.LBB0_577:
	s_waitcnt lgkmcnt(14)
	v_mfma_f32_32x32x16_bf16 v[2:17], v[174:177], v[142:145], v[2:17]
	ds_read_b64_tr_b16 v[142:143], v243 offset:32768
	ds_read_b64_tr_b16 v[144:145], v243 offset:33280
	v_exp_f32_e32 v98, v98
	v_exp_f32_e32 v99, v99
	s_waitcnt lgkmcnt(12)
	v_mfma_f32_32x32x16_bf16 v[50:65], v[174:177], v[138:141], v[50:65]
	ds_read_b64_tr_b16 v[138:139], v243 offset:36864
	ds_read_b64_tr_b16 v[140:141], v243 offset:37376
	v_exp_f32_e32 v100, v100
	v_exp_f32_e32 v101, v101
	v_mfma_f32_32x32x16_bf16 v[2:17], v[170:173], v[134:137], v[2:17]
	ds_read_b64_tr_b16 v[134:135], v243 offset:33792
	ds_read_b64_tr_b16 v[136:137], v243 offset:34304
	v_exp_f32_e32 v102, v102
	v_exp_f32_e32 v103, v103
	s_waitcnt lgkmcnt(14)
	v_mfma_f32_32x32x16_bf16 v[50:65], v[170:173], v[130:133], v[50:65]
	ds_read_b64_tr_b16 v[130:131], v243 offset:37888
	ds_read_b64_tr_b16 v[132:133], v243 offset:38400
	v_exp_f32_e32 v104, v104
	v_exp_f32_e32 v105, v105
	s_waitcnt lgkmcnt(14)
	v_mfma_f32_32x32x16_bf16 v[2:17], v[166:169], v[126:129], v[2:17]
	ds_read_b64_tr_b16 v[126:127], v243 offset:34816
	ds_read_b64_tr_b16 v[128:129], v243 offset:35328
	v_exp_f32_e32 v106, v106
	v_exp_f32_e32 v107, v107
	s_waitcnt lgkmcnt(12)
	v_mfma_f32_32x32x16_bf16 v[50:65], v[166:169], v[122:125], v[50:65]
	ds_read_b64_tr_b16 v[122:123], v243 offset:38912
	ds_read_b64_tr_b16 v[124:125], v243 offset:39424
	v_exp_f32_e32 v108, v108
	v_exp_f32_e32 v109, v109
	v_mfma_f32_32x32x16_bf16 v[2:17], v[162:165], v[118:121], v[2:17]
	ds_read_b64_tr_b16 v[118:119], v243 offset:35840
	ds_read_b64_tr_b16 v[120:121], v243 offset:36352
	v_exp_f32_e32 v110, v110
	v_exp_f32_e32 v111, v111
	s_waitcnt lgkmcnt(14)
	v_mfma_f32_32x32x16_bf16 v[50:65], v[162:165], v[114:117], v[50:65]
	ds_read_b64_tr_b16 v[214:215], v243 offset:39936
	ds_read_b64_tr_b16 v[216:217], v243 offset:40448
	v_exp_f32_e32 v112, v112
	v_exp_f32_e32 v113, v113
	s_waitcnt lgkmcnt(14)
	v_mfma_f32_32x32x16_bf16 v[34:49], v[174:177], v[142:145], v[34:49]
	v_exp_f32_e32 v82, v82
	v_exp_f32_e32 v83, v83
	s_waitcnt lgkmcnt(12)
	v_mfma_f32_32x32x16_bf16 v[18:33], v[174:177], v[138:141], v[18:33]
	v_exp_f32_e32 v84, v84
	v_exp_f32_e32 v85, v85
	v_add_u32_e32 v138, s57, v240
	ds_read_b128 v[114:117], v138
	ds_read_b128 v[198:201], v138 offset:512
	s_waitcnt lgkmcnt(12)
	v_mfma_f32_32x32x16_bf16 v[34:49], v[170:173], v[134:137], v[34:49]
	v_exp_f32_e32 v86, v86
	v_exp_f32_e32 v87, v87
	ds_read_b128 v[202:205], v138 offset:2048
	ds_read_b128 v[194:197], v138 offset:2560
	s_waitcnt lgkmcnt(12)
	v_mfma_f32_32x32x16_bf16 v[18:33], v[170:173], v[130:133], v[18:33]
	v_exp_f32_e32 v88, v88
	v_exp_f32_e32 v89, v89
	ds_read_b128 v[158:161], v138 offset:4096
	ds_read_b128 v[154:157], v138 offset:4608
	s_waitcnt lgkmcnt(12)
	v_mfma_f32_32x32x16_bf16 v[34:49], v[166:169], v[126:129], v[34:49]
	v_exp_f32_e32 v90, v90
	v_exp_f32_e32 v91, v91
	ds_read_b128 v[150:153], v138 offset:6144
	ds_read_b128 v[146:149], v138 offset:6656
	s_waitcnt lgkmcnt(12)
	v_mfma_f32_32x32x16_bf16 v[18:33], v[166:169], v[122:125], v[18:33]
	v_exp_f32_e32 v92, v92
	v_exp_f32_e32 v93, v93
	s_waitcnt lgkmcnt(10)
	v_mfma_f32_32x32x16_bf16 v[34:49], v[162:165], v[118:121], v[34:49]
	v_exp_f32_e32 v94, v94
	v_exp_f32_e32 v95, v95
	s_add_u32 s66, s27, s4
	s_addc_u32 s67, s35, s5
	s_add_u32 s66, s66, 0x62d8800
	s_addc_u32 s67, s67, 0
	s_add_i32 s8, s10, s28
	s_mov_b32 m0, s8
	s_nop 0
	global_load_lds_dwordx4 v0, s[66:67]
	s_waitcnt lgkmcnt(8)
	v_mfma_f32_32x32x16_bf16 v[18:33], v[162:165], v[214:217], v[18:33]
	v_exp_f32_e32 v96, v96
	v_exp_f32_e32 v97, v97
	s_addk_i32 s8, 0x1f80
	s_mov_b32 m0, s8
	s_nop 0
	global_load_lds_dwordx4 v0, s[66:67] offset:128
	s_waitcnt vmcnt(3) lgkmcnt(0)
	s_barrier
	s_andn2_b64 vcc, exec, s[6:7]
	s_cbranch_vccnz .LBB0_579
	s_waitcnt lgkmcnt(0)
	v_add_u32_e32 v130, s36, v241
	ds_read_b128 v[118:121], v130 offset:96
	ds_read_b128 v[122:125], v130 offset:64
	ds_read_b128 v[126:129], v130 offset:32
	ds_read_b128 v[130:133], v130
	s_waitcnt lgkmcnt(3)
	v_pk_mul_f32 v[14:15], v[14:15], v[118:119]
	s_waitcnt lgkmcnt(2)
	v_pk_mul_f32 v[10:11], v[10:11], v[122:123]
	s_waitcnt lgkmcnt(1)
	v_pk_mul_f32 v[6:7], v[6:7], v[126:127]
	v_pk_mul_f32 v[16:17], v[16:17], v[120:121]
	v_pk_mul_f32 v[12:13], v[12:13], v[124:125]
	v_pk_mul_f32 v[8:9], v[8:9], v[128:129]
	s_waitcnt lgkmcnt(0)
	v_pk_mul_f32 v[4:5], v[4:5], v[132:133]
	v_pk_mul_f32 v[2:3], v[2:3], v[130:131]
	v_pk_mul_f32 v[62:63], v[62:63], v[118:119]
	v_pk_mul_f32 v[58:59], v[58:59], v[122:123]
	v_pk_mul_f32 v[54:55], v[54:55], v[126:127]
	v_pk_mul_f32 v[64:65], v[64:65], v[120:121]
	v_pk_mul_f32 v[60:61], v[60:61], v[124:125]
	v_pk_mul_f32 v[56:57], v[56:57], v[128:129]
	v_pk_mul_f32 v[52:53], v[52:53], v[132:133]
	v_pk_mul_f32 v[50:51], v[50:51], v[130:131]
	v_pk_mul_f32 v[46:47], v[46:47], v[118:119]
	v_pk_mul_f32 v[42:43], v[42:43], v[122:123]
	v_pk_mul_f32 v[38:39], v[38:39], v[126:127]
	v_pk_mul_f32 v[48:49], v[48:49], v[120:121]
	v_pk_mul_f32 v[44:45], v[44:45], v[124:125]
	v_pk_mul_f32 v[40:41], v[40:41], v[128:129]
	v_pk_mul_f32 v[36:37], v[36:37], v[132:133]
	v_pk_mul_f32 v[34:35], v[34:35], v[130:131]
	v_pk_mul_f32 v[30:31], v[30:31], v[118:119]
	v_pk_mul_f32 v[26:27], v[26:27], v[122:123]
	v_pk_mul_f32 v[22:23], v[22:23], v[126:127]
	v_pk_mul_f32 v[32:33], v[32:33], v[120:121]
	v_pk_mul_f32 v[28:29], v[28:29], v[124:125]
	v_pk_mul_f32 v[24:25], v[24:25], v[128:129]
	v_pk_mul_f32 v[20:21], v[20:21], v[132:133]
	v_pk_mul_f32 v[18:19], v[18:19], v[130:131]

.LBB0_682:
	v_add_u32_e32 v187, s6, v211
	ds_read_b64_tr_b16 v[178:179], v187 offset:24576
	ds_read_b64_tr_b16 v[180:181], v187 offset:25088
	v_mfma_f32_32x32x16_bf16 v[98:113], v[82:85], v[158:161], v[34:49]
	v_add_f32_e32 v86, v66, v67
	v_add_f32_e32 v86, v68, v86
	v_add_f32_e32 v86, v69, v86
	v_add_f32_e32 v86, v70, v86
	v_add_f32_e32 v86, v71, v86
	v_cvt_pk_bf16_f32 v150, v66, v67
	v_cvt_pk_bf16_f32 v151, v68, v69
	ds_read_b64_tr_b16 v[174:175], v187 offset:28672
	ds_read_b64_tr_b16 v[176:177], v187 offset:29184
	v_add_f32_e32 v66, v72, v86
	v_mfma_f32_32x32x16_bf16 v[82:97], v[166:169], v[158:161], v[34:49]
	v_add_f32_e32 v66, v73, v66
	v_add_f32_e32 v66, v74, v66
	v_add_f32_e32 v130, v75, v66
	v_cvt_pk_bf16_f32 v152, v70, v71
	v_cvt_pk_bf16_f32 v153, v72, v73
	ds_read_b64_tr_b16 v[66:67], v187 offset:25600
	ds_read_b64_tr_b16 v[68:69], v187 offset:26112
	v_mfma_f32_32x32x16_bf16 v[98:113], v[170:173], v[154:157], v[98:113]
	v_add_f32_e32 v70, v76, v130
	v_add_f32_e32 v70, v77, v70
	v_add_f32_e32 v70, v78, v70
	v_add_f32_e32 v130, v79, v70
	v_cvt_pk_bf16_f32 v142, v74, v75
	v_cvt_pk_bf16_f32 v143, v76, v77
	ds_read_b64_tr_b16 v[70:71], v187 offset:29696
	ds_read_b64_tr_b16 v[72:73], v187 offset:30208
	v_mfma_f32_32x32x16_bf16 v[82:97], v[162:165], v[154:157], v[82:97]
	v_add_f32_e32 v74, v80, v130
	v_add_f32_e32 v74, v81, v74
	v_add_f32_e32 v74, v50, v74
	v_add_f32_e32 v130, v51, v74
	v_cvt_pk_bf16_f32 v144, v78, v79
	v_cvt_pk_bf16_f32 v145, v80, v81
	ds_read_b64_tr_b16 v[74:75], v187 offset:26624
	ds_read_b64_tr_b16 v[76:77], v187 offset:27136
	v_mfma_f32_32x32x16_bf16 v[98:113], v[126:129], v[146:149], v[98:113]
	v_add_f32_e32 v78, v52, v130
	v_add_f32_e32 v78, v53, v78
	v_add_f32_e32 v78, v54, v78
	v_add_f32_e32 v78, v55, v78
	v_cvt_pk_bf16_f32 v134, v50, v51
	v_cvt_pk_bf16_f32 v135, v52, v53
	ds_read_b64_tr_b16 v[50:51], v187 offset:30720
	ds_read_b64_tr_b16 v[52:53], v187 offset:31232
	v_mfma_f32_32x32x16_bf16 v[82:97], v[122:125], v[146:149], v[82:97]
	v_add_f32_e32 v78, v56, v78
	v_add_f32_e32 v78, v57, v78
	v_add_f32_e32 v78, v58, v78
	v_add_f32_e32 v78, v59, v78
	v_cvt_pk_bf16_f32 v136, v54, v55
	v_cvt_pk_bf16_f32 v137, v56, v57
	ds_read_b64_tr_b16 v[54:55], v187 offset:27648
	ds_read_b64_tr_b16 v[56:57], v187 offset:28160
	v_mfma_f32_32x32x16_bf16 v[98:113], v[118:121], v[138:141], v[98:113]
	v_add_f32_e32 v78, v60, v78
	v_add_f32_e32 v78, v61, v78
	v_add_f32_e32 v78, v62, v78
	v_add_f32_e32 v78, v63, v78
	v_cvt_pk_bf16_f32 v130, v58, v59
	v_cvt_pk_bf16_f32 v131, v60, v61
	ds_read_b64_tr_b16 v[58:59], v187 offset:31744
	ds_read_b64_tr_b16 v[60:61], v187 offset:32256
	v_mfma_f32_32x32x16_bf16 v[82:97], v[114:117], v[138:141], v[82:97]
	v_add_f32_e32 v78, v64, v78
	v_add_f32_e32 v78, v65, v78
	v_cvt_pk_bf16_f32 v132, v62, v63
	v_cvt_pk_bf16_f32 v133, v64, v65
	v_add_f32_e32 v186, v186, v78
	v_max3_f32 v62, v98, v99, v100
	v_max3_f32 v63, v101, v102, v103
	v_max3_f32 v62, v62, v104, v105
	v_max3_f32 v63, v63, v106, v107
	v_max3_f32 v62, v62, v108, v109
	v_max3_f32 v63, v63, v110, v111
	v_max3_f32 v62, v62, v112, v113
	v_max3_f32 v63, v63, v82, v83
	v_max3_f32 v62, v62, v84, v85
	v_max3_f32 v63, v63, v86, v87
	v_max3_f32 v62, v62, v88, v89
	v_max3_f32 v63, v63, v90, v91
	v_max3_f32 v62, v62, v92, v93
	v_max3_f32 v63, v63, v94, v95
	v_max3_f32 v62, v62, v96, v97
	v_max_f32_e32 v62, v62, v63
	v_mov_b32_e32 v63, v62
	s_nop 1
	v_permlane32_swap_b32_e32 v62, v63
	v_max_f32_e32 v62, v62, v63
	v_cmp_lt_f32_e32 vcc, s15, v62
	s_cmp_lg_u64 vcc, 0
	s_cselect_b64 s[6:7], -1, 0
	s_cbranch_vccnz .LBB0_690
.LBB0_683:
	s_waitcnt lgkmcnt(14)
	v_mfma_f32_32x32x16_bf16 v[2:17], v[150:153], v[178:181], v[2:17]
	v_exp_f32_e32 v98, v98
	v_exp_f32_e32 v99, v99
	v_exp_f32_e32 v100, v100
	v_exp_f32_e32 v101, v101
	s_waitcnt lgkmcnt(12)
	v_mfma_f32_32x32x16_bf16 v[18:33], v[150:153], v[174:177], v[18:33]
	v_exp_f32_e32 v102, v102
	v_exp_f32_e32 v103, v103
	v_exp_f32_e32 v104, v104
	v_exp_f32_e32 v105, v105
	s_add_i32 m0, s26, s20
	s_add_u32 s8, s100, 0xfffb8000
	s_addc_u32 s9, s101, -1
	global_load_lds_dwordx4 v184, s[8:9]
	v_add_u32_e32 v78, s23, v210
	ds_read_b128 v[62:65], v78
	ds_read_b128 v[174:177], v78 offset:512
	s_waitcnt lgkmcnt(12)
	v_mfma_f32_32x32x16_bf16 v[2:17], v[142:145], v[66:69], v[2:17]
	v_exp_f32_e32 v106, v106
	v_exp_f32_e32 v107, v107
	v_exp_f32_e32 v108, v108
	v_exp_f32_e32 v109, v109
	ds_read_b128 v[178:181], v78 offset:2048
	ds_read_b128 v[170:173], v78 offset:2560
	s_waitcnt lgkmcnt(12)
	v_mfma_f32_32x32x16_bf16 v[18:33], v[142:145], v[70:73], v[18:33]
	v_exp_f32_e32 v110, v110
	v_exp_f32_e32 v111, v111
	v_exp_f32_e32 v112, v112
	v_exp_f32_e32 v113, v113
	ds_read_b128 v[166:169], v78 offset:4096
	ds_read_b128 v[162:165], v78 offset:4608
	s_waitcnt lgkmcnt(12)
	v_mfma_f32_32x32x16_bf16 v[2:17], v[134:137], v[74:77], v[2:17]
	v_exp_f32_e32 v82, v82
	v_exp_f32_e32 v83, v83
	v_exp_f32_e32 v84, v84
	v_exp_f32_e32 v85, v85
	ds_read_b128 v[126:129], v78 offset:6144
	ds_read_b128 v[122:125], v78 offset:6656
	s_waitcnt lgkmcnt(12)
	v_mfma_f32_32x32x16_bf16 v[18:33], v[134:137], v[50:53], v[18:33]
	v_exp_f32_e32 v86, v86
	v_exp_f32_e32 v87, v87
	v_exp_f32_e32 v88, v88
	v_exp_f32_e32 v89, v89
	s_waitcnt lgkmcnt(10)
	v_mfma_f32_32x32x16_bf16 v[2:17], v[130:133], v[54:57], v[2:17]
	v_exp_f32_e32 v90, v90
	v_exp_f32_e32 v91, v91
	v_exp_f32_e32 v92, v92
	v_exp_f32_e32 v93, v93
	s_waitcnt lgkmcnt(8)
	v_mfma_f32_32x32x16_bf16 v[18:33], v[130:133], v[58:61], v[18:33]
	v_exp_f32_e32 v94, v94
	v_exp_f32_e32 v95, v95
	v_exp_f32_e32 v96, v96
	v_exp_f32_e32 v97, v97
	s_add_i32 m0, s23, s19
	s_add_u32 s8, s66, 0xfffb8000
	s_addc_u32 s9, s67, -1
	global_load_lds_dwordx4 v182, s[8:9]
	s_waitcnt vmcnt(2) lgkmcnt(0)
	s_barrier
	s_andn2_b64 vcc, exec, s[6:7]
	s_cbranch_vccnz .LBB0_685
	s_waitcnt lgkmcnt(0)
	v_add_u32_e32 v66, s21, v212
	ds_read_b128 v[50:53], v66 offset:49248
	ds_read_b128 v[54:57], v66 offset:49216
	ds_read_b128 v[58:61], v66 offset:49184
	ds_read_b128 v[66:69], v66 offset:49152
	s_waitcnt lgkmcnt(3)
	v_pk_mul_f32 v[14:15], v[14:15], v[50:51]
	s_waitcnt lgkmcnt(2)
	v_pk_mul_f32 v[10:11], v[10:11], v[54:55]
	s_waitcnt lgkmcnt(1)
	v_pk_mul_f32 v[6:7], v[6:7], v[58:59]
	v_pk_mul_f32 v[16:17], v[16:17], v[52:53]
	v_pk_mul_f32 v[12:13], v[12:13], v[56:57]
	v_pk_mul_f32 v[8:9], v[8:9], v[60:61]
	s_waitcnt lgkmcnt(0)
	v_pk_mul_f32 v[4:5], v[4:5], v[68:69]
	v_pk_mul_f32 v[2:3], v[2:3], v[66:67]
	v_pk_mul_f32 v[30:31], v[30:31], v[50:51]
	v_pk_mul_f32 v[26:27], v[26:27], v[54:55]
	v_pk_mul_f32 v[22:23], v[22:23], v[58:59]
	v_pk_mul_f32 v[32:33], v[32:33], v[52:53]
	v_pk_mul_f32 v[28:29], v[28:29], v[56:57]
	v_pk_mul_f32 v[24:25], v[24:25], v[60:61]
	v_pk_mul_f32 v[20:21], v[20:21], v[68:69]
	v_pk_mul_f32 v[18:19], v[18:19], v[66:67]
; #define WAIT_BAR(N) asm volatile("s_waitcnt vmcnt(" #N ") lgkmcnt(0)\n\ts_barrier":::"memory")
;   #define RESC() do{ if(resc){ asm volatile("s_waitcnt lgkmcnt(0)":::"memory"); \
;       _Pragma("unroll") for(int d_=0;d_<2;++d_) _Pragma("unroll") for(int r=0;r<16;++r)o[d_][r]*=wsf[crow(r,hi)]; } }while(0)
;   #define ROT() do{sl_prev=sl_cur;sl_cur=sl_next;sl_next=(sl_next==(NSLOT-1)*SLOTB)?0:sl_next+SLOTB;}while(0)
;   #define RESC() do{ if(resc){ asm volatile("s_waitcnt lgkmcnt(0)":::"memory"); \
;       _Pragma("unroll") for(int d_=0;d_<4;++d_) _Pragma("unroll") for(int r=0;r<16;++r)o[d_][r]*=wsf[crow(r,hi)]; } }while(0)
;   #define ROT() do{sl_prev=sl_cur;sl_cur=sl_next;sl_next=(sl_next==(NSLOT-1)*SLOTB)?0:sl_next+SLOTB;}while(0)
; template<int THRL> __device__ __forceinline__ void attn_unit(const bf16*Qblk,const bf16*__restrict__ Kh,const bf16*__restrict__ Vh,bf16*Oblk,const int po,const int NT,char*shm){
;     ...
;   int t=1;
;     ...
;   for(;t+5<NT;t+=2){
;     STEP(pB0,pB1,pA0,pA1,t,true,true,true);     WAIT_BAR(2); RESC(); ROT();
;     STEP(pA0,pA1,pB0,pB1,t+1,true,true,true);   WAIT_BAR(2); RESC(); ROT();
.LBB0_685:
	s_add_i32 s6, s23, 0x2000
	s_cmpk_lg_i32 s23, 0x4000
	s_cselect_b32 s24, s6, 0
	v_add_u32_e32 v187, s26, v211
	ds_read_b64_tr_b16 v[118:119], v187 offset:24576
	ds_read_b64_tr_b16 v[120:121], v187 offset:25088
	v_mfma_f32_32x32x16_bf16 v[66:81], v[62:65], v[158:161], v[34:49]
	v_add_f32_e32 v50, v98, v99
	v_add_f32_e32 v50, v100, v50
	v_add_f32_e32 v50, v101, v50
	v_add_f32_e32 v50, v102, v50
	v_add_f32_e32 v50, v103, v50
	v_cvt_pk_bf16_f32 v150, v98, v99
	v_cvt_pk_bf16_f32 v151, v100, v101
	ds_read_b64_tr_b16 v[114:115], v187 offset:28672
	ds_read_b64_tr_b16 v[116:117], v187 offset:29184
	v_add_f32_e32 v50, v104, v50
	v_add_f32_e32 v50, v105, v50
	v_add_f32_e32 v50, v106, v50
	v_add_f32_e32 v130, v107, v50
	v_mfma_f32_32x32x16_bf16 v[50:65], v[174:177], v[158:161], v[34:49]
	v_cvt_pk_bf16_f32 v152, v102, v103
	v_cvt_pk_bf16_f32 v153, v104, v105
	ds_read_b64_tr_b16 v[98:99], v187 offset:25600
	ds_read_b64_tr_b16 v[100:101], v187 offset:26112
	v_mfma_f32_32x32x16_bf16 v[66:81], v[178:181], v[154:157], v[66:81]
	v_add_f32_e32 v102, v108, v130
	v_add_f32_e32 v102, v109, v102
	v_add_f32_e32 v102, v110, v102
	v_add_f32_e32 v130, v111, v102
	v_cvt_pk_bf16_f32 v142, v106, v107
	v_cvt_pk_bf16_f32 v143, v108, v109
	ds_read_b64_tr_b16 v[102:103], v187 offset:29696
	ds_read_b64_tr_b16 v[104:105], v187 offset:30208
	v_mfma_f32_32x32x16_bf16 v[50:65], v[170:173], v[154:157], v[50:65]
	v_add_f32_e32 v106, v112, v130
	v_add_f32_e32 v106, v113, v106
	v_add_f32_e32 v106, v82, v106
	v_add_f32_e32 v130, v83, v106
	v_cvt_pk_bf16_f32 v144, v110, v111
	v_cvt_pk_bf16_f32 v145, v112, v113
	ds_read_b64_tr_b16 v[106:107], v187 offset:26624
	ds_read_b64_tr_b16 v[108:109], v187 offset:27136
	v_mfma_f32_32x32x16_bf16 v[66:81], v[166:169], v[146:149], v[66:81]
	v_add_f32_e32 v110, v84, v130
	v_add_f32_e32 v110, v85, v110
	v_add_f32_e32 v110, v86, v110
	v_add_f32_e32 v130, v87, v110
	v_cvt_pk_bf16_f32 v134, v82, v83
	v_cvt_pk_bf16_f32 v135, v84, v85
	ds_read_b64_tr_b16 v[110:111], v187 offset:30720
	ds_read_b64_tr_b16 v[112:113], v187 offset:31232
	v_mfma_f32_32x32x16_bf16 v[50:65], v[162:165], v[146:149], v[50:65]
	v_add_f32_e32 v82, v88, v130
	v_add_f32_e32 v82, v89, v82
	v_add_f32_e32 v82, v90, v82
	v_add_f32_e32 v82, v91, v82
	v_cvt_pk_bf16_f32 v136, v86, v87
	v_cvt_pk_bf16_f32 v137, v88, v89
	ds_read_b64_tr_b16 v[86:87], v187 offset:27648
	ds_read_b64_tr_b16 v[88:89], v187 offset:28160
	v_mfma_f32_32x32x16_bf16 v[66:81], v[126:129], v[138:141], v[66:81]
	v_add_f32_e32 v82, v92, v82
	v_add_f32_e32 v82, v93, v82
	v_add_f32_e32 v82, v94, v82
	v_add_f32_e32 v82, v95, v82
	v_cvt_pk_bf16_f32 v130, v90, v91
	v_cvt_pk_bf16_f32 v131, v92, v93
	ds_read_b64_tr_b16 v[90:91], v187 offset:31744
	ds_read_b64_tr_b16 v[92:93], v187 offset:32256
	v_mfma_f32_32x32x16_bf16 v[50:65], v[122:125], v[138:141], v[50:65]
	v_add_f32_e32 v82, v96, v82
	v_add_f32_e32 v82, v97, v82
	v_cvt_pk_bf16_f32 v132, v94, v95
	v_cvt_pk_bf16_f32 v133, v96, v97
	v_add_f32_e32 v186, v186, v82
	v_max3_f32 v82, v66, v67, v68
	v_max3_f32 v83, v69, v70, v71
	v_max3_f32 v82, v82, v72, v73
	v_max3_f32 v83, v83, v74, v75
	v_max3_f32 v82, v82, v76, v77
	v_max3_f32 v83, v83, v78, v79
	v_max3_f32 v82, v82, v80, v81
	v_max3_f32 v83, v83, v50, v51
	v_max3_f32 v82, v82, v52, v53
	v_max3_f32 v83, v83, v54, v55
	v_max3_f32 v82, v82, v56, v57
	v_max3_f32 v83, v83, v58, v59
	v_max3_f32 v82, v82, v60, v61
	v_max3_f32 v83, v83, v62, v63
	v_max3_f32 v82, v82, v64, v65
	v_max_f32_e32 v82, v82, v83
	v_mov_b32_e32 v83, v82
	s_nop 1
	v_permlane32_swap_b32_e32 v82, v83
	v_max_f32_e32 v82, v82, v83
	v_cmp_lt_f32_e32 vcc, s15, v82
	s_cmp_lg_u64 vcc, 0
	s_cselect_b64 s[6:7], -1, 0
	s_cbranch_vccnz .LBB0_693
.LBB0_686:
	s_waitcnt lgkmcnt(14)
	v_mfma_f32_32x32x16_bf16 v[2:17], v[150:153], v[118:121], v[2:17]
	v_exp_f32_e32 v66, v66
	v_exp_f32_e32 v67, v67
	v_exp_f32_e32 v68, v68
	v_exp_f32_e32 v69, v69
	s_waitcnt lgkmcnt(12)
	v_mfma_f32_32x32x16_bf16 v[18:33], v[150:153], v[114:117], v[18:33]
	v_exp_f32_e32 v70, v70
	v_exp_f32_e32 v71, v71
	v_exp_f32_e32 v72, v72
	v_exp_f32_e32 v73, v73
	s_add_i32 m0, s23, s20
	s_nop 0
	global_load_lds_dwordx4 v184, s[100:101]
	v_add_u32_e32 v94, s24, v210
	ds_read_b128 v[82:85], v94
	ds_read_b128 v[166:169], v94 offset:512
	s_waitcnt lgkmcnt(12)
	v_mfma_f32_32x32x16_bf16 v[2:17], v[142:145], v[98:101], v[2:17]
	v_exp_f32_e32 v74, v74
	v_exp_f32_e32 v75, v75
	v_exp_f32_e32 v76, v76
	v_exp_f32_e32 v77, v77
	ds_read_b128 v[170:173], v94 offset:2048
	ds_read_b128 v[162:165], v94 offset:2560
	s_waitcnt lgkmcnt(12)
	v_mfma_f32_32x32x16_bf16 v[18:33], v[142:145], v[102:105], v[18:33]
	v_exp_f32_e32 v78, v78
	v_exp_f32_e32 v79, v79
	v_exp_f32_e32 v80, v80
	v_exp_f32_e32 v81, v81
	ds_read_b128 v[126:129], v94 offset:4096
	ds_read_b128 v[122:125], v94 offset:4608
	s_waitcnt lgkmcnt(12)
	v_mfma_f32_32x32x16_bf16 v[2:17], v[134:137], v[106:109], v[2:17]
	v_exp_f32_e32 v50, v50
	v_exp_f32_e32 v51, v51
	v_exp_f32_e32 v52, v52
	v_exp_f32_e32 v53, v53
	ds_read_b128 v[118:121], v94 offset:6144
	ds_read_b128 v[114:117], v94 offset:6656
	s_waitcnt lgkmcnt(12)
	v_mfma_f32_32x32x16_bf16 v[18:33], v[134:137], v[110:113], v[18:33]
	v_exp_f32_e32 v54, v54
	v_exp_f32_e32 v55, v55
	v_exp_f32_e32 v56, v56
	v_exp_f32_e32 v57, v57
	s_waitcnt lgkmcnt(10)
	v_mfma_f32_32x32x16_bf16 v[2:17], v[130:133], v[86:89], v[2:17]
	v_exp_f32_e32 v58, v58
	v_exp_f32_e32 v59, v59
	v_exp_f32_e32 v60, v60
	v_exp_f32_e32 v61, v61
	s_waitcnt lgkmcnt(8)
	v_mfma_f32_32x32x16_bf16 v[18:33], v[130:133], v[90:93], v[18:33]
	v_exp_f32_e32 v62, v62
	v_exp_f32_e32 v63, v63
	v_exp_f32_e32 v64, v64
	v_exp_f32_e32 v65, v65
	s_add_i32 m0, s24, s19
	s_nop 0
	global_load_lds_dwordx4 v182, s[66:67]
	s_waitcnt vmcnt(2) lgkmcnt(0)
	s_barrier
	s_andn2_b64 vcc, exec, s[6:7]
	s_cbranch_vccnz .LBB0_688
	s_waitcnt lgkmcnt(0)
	v_add_u32_e32 v98, s21, v212
	ds_read_b128 v[86:89], v98 offset:49248
	ds_read_b128 v[90:93], v98 offset:49216
	ds_read_b128 v[94:97], v98 offset:49152
	ds_read_b128 v[98:101], v98 offset:49184
	s_waitcnt lgkmcnt(3)
	v_pk_mul_f32 v[16:17], v[16:17], v[88:89]
	v_pk_mul_f32 v[14:15], v[14:15], v[86:87]
	s_waitcnt lgkmcnt(2)
	v_pk_mul_f32 v[12:13], v[12:13], v[92:93]
	v_pk_mul_f32 v[10:11], v[10:11], v[90:91]
	s_waitcnt lgkmcnt(0)
	v_pk_mul_f32 v[8:9], v[8:9], v[100:101]
	v_pk_mul_f32 v[6:7], v[6:7], v[98:99]
	v_pk_mul_f32 v[4:5], v[4:5], v[96:97]
	v_pk_mul_f32 v[2:3], v[2:3], v[94:95]
	v_pk_mul_f32 v[32:33], v[32:33], v[88:89]
	v_pk_mul_f32 v[30:31], v[30:31], v[86:87]
	v_pk_mul_f32 v[28:29], v[28:29], v[92:93]
	v_pk_mul_f32 v[26:27], v[26:27], v[90:91]
	v_pk_mul_f32 v[24:25], v[24:25], v[100:101]
	v_pk_mul_f32 v[22:23], v[22:23], v[98:99]
	v_pk_mul_f32 v[20:21], v[20:21], v[96:97]
	v_pk_mul_f32 v[18:19], v[18:19], v[94:95]
